# mix_state RetNet items: keep the per-head log-decay in a register instead of re-loading it (with a full vmcnt(0) wait) after each lane-0 decay store
# speedup vs baseline: 1.0102x; 1.0003x over previous
.LBB0_682:
	s_nop 0
	global_load_dword v106, v49, s[86:87]
	s_waitcnt vmcnt(6)
	v_and_b32_e32 v108, 0xffff0000, v32
	s_mul_i32 s0, s13, 36
	s_ashr_i32 s4, s12, 31
	v_lshlrev_b32_e32 v107, 16, v32
	s_waitcnt vmcnt(1)
	v_mul_f32_e32 v115, v103, v108
	s_mul_hi_i32 s1, s13, 36
	s_add_u32 s0, s0, s12
	v_and_b32_e32 v110, 0xffff0000, v33
	v_fma_f32 v115, v102, v107, -v115
	v_mul_f32_e32 v102, v102, v108
	s_addc_u32 s1, s1, s4
	v_lshlrev_b32_e32 v109, 16, v33
	v_fmac_f32_e32 v102, v103, v107
	v_mul_f32_e32 v103, v105, v110
	s_lshl_b64 s[0:1], s[0:1], 3
	v_and_b32_e32 v112, 0xffff0000, v34
	v_fma_f32 v103, v104, v109, -v103
	v_mul_f32_e32 v104, v104, v110
	s_add_u32 s0, s0, s22
	v_lshlrev_b32_e32 v111, 16, v34
	v_fmac_f32_e32 v104, v105, v109
	v_mul_f32_e32 v105, v99, v112
	s_addc_u32 s1, s1, s23
	v_and_b32_e32 v114, 0xffff0000, v35
	v_fma_f32 v105, v98, v111, -v105
	v_mul_f32_e32 v98, v98, v112
	s_mulk_i32 s1, 0xc0
	s_mul_hi_u32 s4, s0, 0xc0
	v_lshlrev_b32_e32 v113, 16, v35
	v_fmac_f32_e32 v98, v99, v111
	v_mul_f32_e32 v99, v101, v114
	s_add_i32 s89, s4, s1
	s_mul_i32 s88, s0, 0xc0
	v_fma_f32 v99, v100, v113, -v99
	v_mul_f32_e32 v100, v100, v114
	s_add_u32 s0, s16, s88
	v_fmac_f32_e32 v100, v101, v113
	s_addc_u32 s1, s17, s89
	s_waitcnt vmcnt(0)
	v_mov_b32_e32 v116, v106
	v_mul_f32_e32 v48, v106, v210
	v_mul_f32_e32 v48, 0x3fb8aa3b, v48
	v_exp_f32_e32 v48, v48
	s_nop 0
	v_mul_f32_e32 v101, v115, v48
	v_cvt_pk_bf16_f32 v101, v101, s0
	ds_write_b16 v208, v101 offset:55296
	v_mul_f32_e32 v101, v102, v48
	v_cvt_pk_bf16_f32 v101, v101, s0
	v_mul_f32_e32 v98, v98, v48
	ds_write_b16 v208, v101 offset:55440
	v_mul_f32_e32 v101, v103, v48
	v_cvt_pk_bf16_f32 v98, v98, s0
	v_cvt_pk_bf16_f32 v101, v101, s0
	ds_write_b16 v208, v98 offset:56016
	v_mul_f32_e32 v98, v99, v48
	ds_write_b16 v208, v101 offset:55584
	v_mul_f32_e32 v101, v104, v48
	v_cvt_pk_bf16_f32 v98, v98, s0
	v_cvt_pk_bf16_f32 v101, v101, s0
	ds_write_b16 v208, v98 offset:56160
	v_mul_f32_e32 v98, v100, v48
	ds_write_b16 v208, v101 offset:55728
	v_mul_f32_e32 v101, v105, v48
	v_cvt_pk_bf16_f32 v98, v98, s0
	v_cvt_pk_bf16_f32 v101, v101, s0
	ds_write_b16 v208, v98 offset:56304
	v_mul_f32_e32 v98, 0x42800000, v106
	ds_write_b16 v208, v101 offset:55872
	s_and_saveexec_b64 vcc, s[10:11]
	s_cbranch_execz .LBB0_684
	v_mul_f32_e32 v48, 0x3fb8aa3b, v98
	v_exp_f32_e32 v98, v48
	s_nop 0
	v_mov_b32_e32 v99, v98
	v_mov_b32_e32 v100, v98
	v_mov_b32_e32 v101, v98
	global_store_dwordx4 v49, v[98:101], s[0:1]
	global_store_dwordx4 v49, v[98:101], s[0:1] offset:16
	s_nop 1
	v_mov_b32_e32 v98, v116
	v_mul_f32_e32 v48, v98, v210
	v_mul_f32_e32 v48, 0x3fb8aa3b, v48
	v_exp_f32_e32 v48, v48
	v_mul_f32_e32 v98, 0x42800000, v98
.LBB0_684:
	s_or_b64 exec, exec, vcc
	v_and_b32_e32 v100, 0xffff0000, v36
	v_lshlrev_b32_e32 v99, 16, v36
	v_mul_f32_e32 v107, v95, v100
	v_and_b32_e32 v102, 0xffff0000, v37
	v_fma_f32 v107, v94, v99, -v107
	v_mul_f32_e32 v94, v94, v100
	v_lshlrev_b32_e32 v101, 16, v37
	v_fmac_f32_e32 v94, v95, v99
	v_mul_f32_e32 v95, v97, v102
	v_and_b32_e32 v104, 0xffff0000, v38
	v_fma_f32 v95, v96, v101, -v95
	v_mul_f32_e32 v96, v96, v102
	v_lshlrev_b32_e32 v103, 16, v38
	v_fmac_f32_e32 v96, v97, v101
	v_mul_f32_e32 v97, v79, v104
	v_and_b32_e32 v106, 0xffff0000, v39
	v_fma_f32 v97, v78, v103, -v97
	v_mul_f32_e32 v78, v78, v104
	v_lshlrev_b32_e32 v105, 16, v39
	v_fmac_f32_e32 v78, v79, v103
	v_mul_f32_e32 v79, v81, v106
	v_fma_f32 v79, v80, v105, -v79
	v_mul_f32_e32 v80, v80, v106
	v_fmac_f32_e32 v80, v81, v105
	v_mul_f32_e32 v81, v107, v48
	v_cvt_pk_bf16_f32 v81, v81, s0
	ds_write_b16 v208, v81 offset:56448
	v_mul_f32_e32 v81, v94, v48
	v_cvt_pk_bf16_f32 v81, v81, s0
	ds_write_b16 v208, v81 offset:56592
	v_mul_f32_e32 v81, v95, v48
	v_mul_f32_e32 v78, v78, v48
	v_cvt_pk_bf16_f32 v81, v81, s0
	v_cvt_pk_bf16_f32 v78, v78, s0
	ds_write_b16 v208, v81 offset:56736
	v_mul_f32_e32 v81, v96, v48
	ds_write_b16 v208, v78 offset:57168
	v_mul_f32_e32 v78, v79, v48
	v_cvt_pk_bf16_f32 v81, v81, s0
	v_cvt_pk_bf16_f32 v78, v78, s0
	ds_write_b16 v208, v81 offset:56880
	v_mul_f32_e32 v81, v97, v48
	ds_write_b16 v208, v78 offset:57312
	v_mul_f32_e32 v78, v80, v48
	v_cvt_pk_bf16_f32 v81, v81, s0
	v_cvt_pk_bf16_f32 v78, v78, s0
	ds_write_b16 v208, v81 offset:57024
	ds_write_b16 v208, v78 offset:57456
	s_and_saveexec_b64 vcc, s[10:11]
	s_cbranch_execz .LBB0_686
	v_mul_f32_e32 v48, 0x3fb8aa3b, v98
	v_exp_f32_e32 v78, v48
	s_nop 0
	v_mov_b32_e32 v79, v78
	v_mov_b32_e32 v80, v78
	v_mov_b32_e32 v81, v78
	global_store_dwordx4 v49, v[78:81], s[0:1] offset:32
	global_store_dwordx4 v49, v[78:81], s[0:1] offset:48
	s_nop 1
	v_mov_b32_e32 v78, v116
	v_mul_f32_e32 v48, v78, v210
	v_mul_f32_e32 v48, 0x3fb8aa3b, v48
	v_exp_f32_e32 v48, v48
	v_mul_f32_e32 v98, 0x42800000, v78
.LBB0_686:
	s_or_b64 exec, exec, vcc
	v_and_b32_e32 v79, 0xffff0000, v40
	v_lshlrev_b32_e32 v78, 16, v40
	v_and_b32_e32 v81, 0xffff0000, v41
	v_mul_f32_e32 v99, v91, v79
	v_mul_f32_e32 v79, v90, v79
	v_lshlrev_b32_e32 v80, 16, v41
	v_fma_f32 v99, v90, v78, -v99
	v_fmac_f32_e32 v79, v91, v78
	v_mul_f32_e32 v78, v93, v81
	v_fma_f32 v78, v92, v80, -v78
	v_mul_f32_e32 v81, v92, v81
	v_mul_f32_e32 v78, v78, v48
	v_and_b32_e32 v95, 0xffff0000, v42
	v_fmac_f32_e32 v81, v93, v80
	v_cvt_pk_bf16_f32 v78, v78, s0
	v_lshlrev_b32_e32 v94, 16, v42
	v_mul_f32_e32 v80, v87, v95
	ds_write_b16 v208, v78 offset:57888
	v_mul_f32_e32 v78, v81, v48
	v_fma_f32 v80, v86, v94, -v80
	v_cvt_pk_bf16_f32 v78, v78, s0
	v_mul_f32_e32 v86, v86, v95
	ds_write_b16 v208, v78 offset:58032
	v_mul_f32_e32 v78, v80, v48
	v_and_b32_e32 v97, 0xffff0000, v43
	v_fmac_f32_e32 v86, v87, v94
	v_cvt_pk_bf16_f32 v78, v78, s0
	v_lshlrev_b32_e32 v96, 16, v43
	v_mul_f32_e32 v87, v89, v97
	ds_write_b16 v208, v78 offset:58176
	v_mul_f32_e32 v78, v86, v48
	v_fma_f32 v87, v88, v96, -v87
	v_cvt_pk_bf16_f32 v78, v78, s0
	v_mul_f32_e32 v88, v88, v97
	ds_write_b16 v208, v78 offset:58320
	v_mul_f32_e32 v78, v87, v48
	v_fmac_f32_e32 v88, v89, v96
	v_cvt_pk_bf16_f32 v78, v78, s0
	v_mul_f32_e32 v89, v99, v48
	v_mul_f32_e32 v79, v79, v48
	ds_write_b16 v208, v78 offset:58464
	v_mul_f32_e32 v78, v88, v48
	v_cvt_pk_bf16_f32 v89, v89, s0
	v_cvt_pk_bf16_f32 v79, v79, s0
	v_cvt_pk_bf16_f32 v78, v78, s0
	ds_write_b16 v208, v89 offset:57600
	ds_write_b16 v208, v79 offset:57744
	ds_write_b16 v208, v78 offset:58608
	s_and_saveexec_b64 vcc, s[10:11]
	s_cbranch_execz .LBB0_688
	v_mul_f32_e32 v48, 0x3fb8aa3b, v98
	v_exp_f32_e32 v78, v48
	s_nop 0
	v_mov_b32_e32 v79, v78
	v_mov_b32_e32 v80, v78
	v_mov_b32_e32 v81, v78
	global_store_dwordx4 v49, v[78:81], s[0:1] offset:64
	global_store_dwordx4 v49, v[78:81], s[0:1] offset:80
	s_nop 1
	v_mov_b32_e32 v78, v116
	v_mul_f32_e32 v48, v78, v210
	v_mul_f32_e32 v48, 0x3fb8aa3b, v48
	v_exp_f32_e32 v48, v48
	v_mul_f32_e32 v98, 0x42800000, v78
.LBB0_688:
	s_or_b64 exec, exec, vcc
	v_and_b32_e32 v79, 0xffff0000, v44
	v_lshlrev_b32_e32 v78, 16, v44
	v_and_b32_e32 v81, 0xffff0000, v45
	v_mul_f32_e32 v90, v83, v79
	v_mul_f32_e32 v79, v82, v79
	v_lshlrev_b32_e32 v80, 16, v45
	v_and_b32_e32 v87, 0xffff0000, v46
	v_fma_f32 v90, v82, v78, -v90
	v_fmac_f32_e32 v79, v83, v78
	v_mul_f32_e32 v78, v85, v81
	v_mul_f32_e32 v81, v84, v81
	v_lshlrev_b32_e32 v86, 16, v46
	v_fma_f32 v78, v84, v80, -v78
	v_fmac_f32_e32 v81, v85, v80
	v_mul_f32_e32 v80, v67, v87
	v_and_b32_e32 v89, 0xffff0000, v47
	v_fma_f32 v80, v66, v86, -v80
	v_mul_f32_e32 v66, v66, v87
	v_lshlrev_b32_e32 v88, 16, v47
	v_fmac_f32_e32 v66, v67, v86
	v_mul_f32_e32 v67, v69, v89
	v_fma_f32 v67, v68, v88, -v67
	v_mul_f32_e32 v68, v68, v89
	v_fmac_f32_e32 v68, v69, v88
	v_mul_f32_e32 v69, v90, v48
	v_cvt_pk_bf16_f32 v69, v69, s0
	ds_write_b16 v208, v69 offset:58752
	v_mul_f32_e32 v69, v79, v48
	v_cvt_pk_bf16_f32 v69, v69, s0
	ds_write_b16 v208, v69 offset:58896
	v_mul_f32_e32 v69, v78, v48
	v_mul_f32_e32 v66, v66, v48
	v_cvt_pk_bf16_f32 v69, v69, s0
	v_cvt_pk_bf16_f32 v66, v66, s0
	ds_write_b16 v208, v69 offset:59040
	v_mul_f32_e32 v69, v81, v48
	ds_write_b16 v208, v66 offset:59472
	v_mul_f32_e32 v66, v67, v48
	v_cvt_pk_bf16_f32 v69, v69, s0
	v_cvt_pk_bf16_f32 v66, v66, s0
	ds_write_b16 v208, v69 offset:59184
	v_mul_f32_e32 v69, v80, v48
	ds_write_b16 v208, v66 offset:59616
	v_mul_f32_e32 v66, v68, v48
	v_cvt_pk_bf16_f32 v69, v69, s0
	v_cvt_pk_bf16_f32 v66, v66, s0
	ds_write_b16 v208, v69 offset:59328
	ds_write_b16 v208, v66 offset:59760
	s_and_saveexec_b64 vcc, s[10:11]
	s_cbranch_execz .LBB0_690
	v_mul_f32_e32 v48, 0x3fb8aa3b, v98
	v_exp_f32_e32 v66, v48
	s_nop 0
	v_mov_b32_e32 v67, v66
	v_mov_b32_e32 v68, v66
	v_mov_b32_e32 v69, v66
	global_store_dwordx4 v49, v[66:69], s[0:1] offset:96
	global_store_dwordx4 v49, v[66:69], s[0:1] offset:112
	s_nop 1
	v_mov_b32_e32 v66, v116
	v_mul_f32_e32 v48, v66, v210
	v_mul_f32_e32 v48, 0x3fb8aa3b, v48
	v_exp_f32_e32 v48, v48
	v_mul_f32_e32 v98, 0x42800000, v66
.LBB0_690:
	s_or_b64 exec, exec, vcc
	v_and_b32_e32 v67, 0xffff0000, v50
	v_lshlrev_b32_e32 v66, 16, v50
	v_and_b32_e32 v69, 0xffff0000, v51
	v_mul_f32_e32 v82, v75, v67
	v_mul_f32_e32 v67, v74, v67
	v_lshlrev_b32_e32 v68, 16, v51
	v_fma_f32 v82, v74, v66, -v82
	v_fmac_f32_e32 v67, v75, v66
	v_mul_f32_e32 v66, v77, v69
	v_fma_f32 v66, v76, v68, -v66
	v_mul_f32_e32 v69, v76, v69
	v_mul_f32_e32 v66, v66, v48
	v_and_b32_e32 v79, 0xffff0000, v52
	v_fmac_f32_e32 v69, v77, v68
	v_cvt_pk_bf16_f32 v66, v66, s0
	v_lshlrev_b32_e32 v78, 16, v52
	v_mul_f32_e32 v68, v71, v79
	ds_write_b16 v208, v66 offset:60192
	v_mul_f32_e32 v66, v69, v48
	v_fma_f32 v68, v70, v78, -v68
	v_cvt_pk_bf16_f32 v66, v66, s0
	v_mul_f32_e32 v70, v70, v79
	ds_write_b16 v208, v66 offset:60336
	v_mul_f32_e32 v66, v68, v48
	v_and_b32_e32 v81, 0xffff0000, v53
	v_fmac_f32_e32 v70, v71, v78
	v_cvt_pk_bf16_f32 v66, v66, s0
	v_lshlrev_b32_e32 v80, 16, v53
	v_mul_f32_e32 v71, v73, v81
	ds_write_b16 v208, v66 offset:60480
	v_mul_f32_e32 v66, v70, v48
	v_fma_f32 v71, v72, v80, -v71
	v_cvt_pk_bf16_f32 v66, v66, s0
	v_mul_f32_e32 v72, v72, v81
	ds_write_b16 v208, v66 offset:60624
	v_mul_f32_e32 v66, v71, v48
	v_fmac_f32_e32 v72, v73, v80
	v_cvt_pk_bf16_f32 v66, v66, s0
	v_mul_f32_e32 v73, v82, v48
	v_mul_f32_e32 v67, v67, v48
	ds_write_b16 v208, v66 offset:60768
	v_mul_f32_e32 v66, v72, v48
	v_cvt_pk_bf16_f32 v73, v73, s0
	v_cvt_pk_bf16_f32 v67, v67, s0
	v_cvt_pk_bf16_f32 v66, v66, s0
	ds_write_b16 v208, v73 offset:59904
	ds_write_b16 v208, v67 offset:60048
	ds_write_b16 v208, v66 offset:60912
	s_and_saveexec_b64 vcc, s[10:11]
	s_cbranch_execz .LBB0_692
	v_mul_f32_e32 v48, 0x3fb8aa3b, v98
	v_exp_f32_e32 v66, v48
	s_nop 0
	v_mov_b32_e32 v67, v66
	v_mov_b32_e32 v68, v66
	v_mov_b32_e32 v69, v66
	global_store_dwordx4 v49, v[66:69], s[0:1] offset:128
	global_store_dwordx4 v49, v[66:69], s[0:1] offset:144
	s_nop 1
	v_mov_b32_e32 v66, v116
	v_mul_f32_e32 v48, v66, v210
	v_mul_f32_e32 v48, 0x3fb8aa3b, v48
	v_exp_f32_e32 v48, v48
	v_mul_f32_e32 v98, 0x42800000, v66
